# GEMM-in epilogue: f32->bf16 pair packing via v_cvt_pk_bf16_f32 (same RNE rounding) instead of the 6-op bit trick
# speedup vs baseline: 1.0228x; 1.0021x over previous
; #define UFOR(v, n) _Pragma("unroll") for (int v = 0; v < (n); ++v)
; __device__ __forceinline__ unsigned pk2(float a, float b) { return (unsigned)f2bf(a) | ((unsigned)f2bf(b) << 16); }
; template <int EPI, int K, int KL> ...
;     ...
;   if (EPI == EPI_Z) {
;     u16* dst; int ld, c0;
;     if (bcol < RWC) { dst = e.zrw; ld = RWC; c0 = bcol; } else { dst = e.zcr; ld = CRC; c0 = bcol - RWC; }
;     UFOR(ai, 2) UFOR(bj, 2) UFOR(m, 4) {
;       const f32x4 a = acc[ai][bj][m][0], b = acc[ai][bj][m][1];
;       uint4 pk; pk.x = pk2(a[0], a[1]); pk.y = pk2(a[2], a[3]); pk.z = pk2(b[0], b[1]); pk.w = pk2(b[2], b[3]);
;       *(uint4*)(dst + (size_t)(brow + ai * HALF + wr * 64 + m * 16 + fr) * ld + (c0 + bj * HALF + wc * 32 + fq * 8)) = pk;
;     }
.LBB0_228:
	v_cvt_pk_bf16_f32 v124, v124, v125
	v_cvt_pk_bf16_f32 v125, v126, v127
	v_cvt_pk_bf16_f32 v127, v122, v123
	v_cvt_pk_bf16_f32 v116, v116, v117
	v_cvt_pk_bf16_f32 v117, v118, v119
	v_cvt_pk_bf16_f32 v119, v114, v115
	v_cvt_pk_bf16_f32 v108, v108, v109
	v_cvt_pk_bf16_f32 v109, v110, v111
	v_cvt_pk_bf16_f32 v111, v106, v107
	v_cvt_pk_bf16_f32 v100, v100, v101
	v_cvt_pk_bf16_f32 v101, v102, v103
	v_cvt_pk_bf16_f32 v102, v96, v97
	v_cvt_pk_bf16_f32 v92, v92, v93
	v_cvt_pk_bf16_f32 v93, v94, v95
	v_cvt_pk_bf16_f32 v94, v88, v89
	v_cvt_pk_bf16_f32 v84, v84, v85
	v_cvt_pk_bf16_f32 v85, v86, v87
	v_cvt_pk_bf16_f32 v86, v80, v81
	v_cvt_pk_bf16_f32 v76, v76, v77
	v_cvt_pk_bf16_f32 v77, v78, v79
	v_cvt_pk_bf16_f32 v78, v72, v73
	v_cvt_pk_bf16_f32 v68, v68, v69
	v_cvt_pk_bf16_f32 v69, v70, v71
	v_cvt_pk_bf16_f32 v71, v66, v67
	v_cvt_pk_bf16_f32 v60, v60, v61
	v_cvt_pk_bf16_f32 v61, v62, v63
	v_cvt_pk_bf16_f32 v63, v58, v59
	v_cvt_pk_bf16_f32 v52, v52, v53
	v_cvt_pk_bf16_f32 v53, v54, v55
	v_cvt_pk_bf16_f32 v55, v50, v51
	v_cvt_pk_bf16_f32 v44, v44, v45
	v_cvt_pk_bf16_f32 v45, v46, v47
	v_cvt_pk_bf16_f32 v47, v42, v43
	v_cvt_pk_bf16_f32 v36, v36, v37
	v_cvt_pk_bf16_f32 v37, v38, v39
	v_cvt_pk_bf16_f32 v38, v32, v33
	v_cvt_pk_bf16_f32 v28, v28, v29
	v_cvt_pk_bf16_f32 v29, v30, v31
	v_cvt_pk_bf16_f32 v30, v24, v25
	v_cvt_pk_bf16_f32 v20, v20, v21
	v_cvt_pk_bf16_f32 v21, v22, v23
	v_cvt_pk_bf16_f32 v22, v16, v17
	v_cvt_pk_bf16_f32 v12, v12, v13
	v_cvt_pk_bf16_f32 v13, v14, v15
	v_cvt_pk_bf16_f32 v14, v8, v9
	v_cvt_pk_bf16_f32 v126, v120, v121
	v_cvt_pk_bf16_f32 v118, v112, v113
	v_cvt_pk_bf16_f32 v110, v104, v105
	v_cvt_pk_bf16_f32 v4, v4, v5
	v_cvt_pk_bf16_f32 v5, v6, v7
	v_cvt_pk_bf16_f32 v70, v64, v65
	v_cvt_pk_bf16_f32 v62, v56, v57
	v_cvt_pk_bf16_f32 v54, v48, v49
	v_cvt_pk_bf16_f32 v103, v98, v99
	v_cvt_pk_bf16_f32 v95, v90, v91
	v_cvt_pk_bf16_f32 v87, v82, v83
	v_cvt_pk_bf16_f32 v79, v74, v75
	v_cvt_pk_bf16_f32 v46, v40, v41
	v_cvt_pk_bf16_f32 v39, v34, v35
	v_cvt_pk_bf16_f32 v31, v26, v27
	v_cvt_pk_bf16_f32 v23, v18, v19
	v_cvt_pk_bf16_f32 v15, v10, v11
	v_cvt_pk_bf16_f32 v7, v2, v3
	v_cvt_pk_bf16_f32 v6, v0, v1
	s_add_i32 s15, s46, 0xfffff600
	s_cmp_lt_i32 s14, 10
	s_mov_b32 s18, 0x12d00000
	v_ashrrev_i32_e32 v129, 31, v128
	v_lshl_add_u64 v[130:131], s[44:45], 0, v[132:133]
	s_movk_i32 s14, 0xa00
	s_cselect_b32 s15, s46, s15
	s_cselect_b32 s18, s18, 0x1d000000
	v_lshl_add_u64 v[128:129], v[130:131], 0, v[128:129]
	v_lshlrev_b32_e32 v130, 5, v154
	v_lshlrev_b32_e32 v131, 3, v155
	s_cselect_b32 s14, s14, 0x1200
	s_add_u32 s18, s92, s18
	v_or3_b32 v130, v130, s15, v131
	s_addc_u32 s19, s93, 0
	v_ashrrev_i32_e32 v131, 31, v130
	v_lshl_add_u64 v[130:131], v[130:131], 1, s[18:19]
	v_mad_u64_u32 v[136:137], s[18:19], v128, s14, 0
	v_mov_b32_e32 v128, v137
	v_mad_u64_u32 v[128:129], s[18:19], v129, s14, v[128:129]
	v_mov_b32_e32 v137, v128
	v_lshl_add_u64 v[128:129], v[136:137], 1, v[130:131]
	v_readlane_b32 s18, v254, 59
	v_readlane_b32 s19, v254, 60
	s_lshl_b32 s18, s14, 5
	v_lshl_add_u64 v[120:121], v[128:129], 0, s[18:19]
	v_lshl_add_u64 v[112:113], v[120:121], 0, s[18:19]
	v_lshl_add_u64 v[104:105], v[112:113], 0, s[18:19]
	s_mulk_i32 s14, 0xa0
	s_mov_b32 s15, s19
	v_lshl_add_u64 v[64:65], v[104:105], 0, s[14:15]
	v_lshl_add_u64 v[56:57], v[64:65], 0, s[18:19]
	v_lshl_add_u64 v[48:49], v[56:57], 0, s[18:19]
	v_writelane_b32 v254, s14, 59
	v_writelane_b32 v254, s15, 60
	v_lshl_add_u64 v[40:41], v[48:49], 0, s[18:19]
	s_mov_b64 s[50:51], 0
	s_andn2_b64 vcc, exec, s[40:41]
	s_mov_b32 s14, s7
	s_mov_b64 s[44:45], s[42:43]
	global_store_dwordx4 v[128:129], v[124:127], off
	global_store_dwordx4 v[120:121], v[116:119], off
	global_store_dwordx4 v[112:113], v[108:111], off
	global_store_dwordx4 v[104:105], v[100:103], off
	global_store_dwordx4 v[128:129], v[92:95], off offset:256
	global_store_dwordx4 v[120:121], v[84:87], off offset:256
	global_store_dwordx4 v[112:113], v[76:79], off offset:256
	global_store_dwordx4 v[104:105], v[68:71], off offset:256
	global_store_dwordx4 v[64:65], v[60:63], off
	global_store_dwordx4 v[56:57], v[52:55], off
	global_store_dwordx4 v[48:49], v[44:47], off
	global_store_dwordx4 v[40:41], v[36:39], off
	global_store_dwordx4 v[64:65], v[28:31], off offset:256
	global_store_dwordx4 v[56:57], v[20:23], off offset:256
	global_store_dwordx4 v[48:49], v[12:15], off offset:256
	global_store_dwordx4 v[40:41], v[4:7], off offset:256
	s_cbranch_vccz .LBB0_241
